# v024 + grid barrier: non-leader workgroups poll the top generation word directly (one release hop less)
# speedup vs baseline: 1.0059x; 1.0059x over previous
.LBB0_121:
	s_or_b64 exec, exec, s[10:11]
	v_cvt_f32_u32_e32 v4, v2
	s_waitcnt vmcnt(0)
	v_readfirstlane_b32 s0, v3
	v_sub_u32_e32 v3, 0, v2
	v_rcp_iflag_f32_e32 v4, v4
	v_add_u32_e32 v5, s0, v1
	v_mul_f32_e32 v4, 0x4f7ffffe, v4
	v_cvt_u32_f32_e32 v4, v4
	v_mul_lo_u32 v1, v3, v4
	v_mul_hi_u32 v1, v4, v1
	v_add_u32_e32 v1, v4, v1
	v_mul_hi_u32 v1, v5, v1
	v_mul_lo_u32 v3, v1, v2
	v_sub_u32_e32 v3, v5, v3
	v_add_u32_e32 v4, 1, v1
	v_cmp_ge_u32_e32 vcc, v3, v2
	s_nop 1
	v_cndmask_b32_e32 v1, v1, v4, vcc
	v_sub_u32_e32 v4, v3, v2
	v_cndmask_b32_e32 v3, v3, v4, vcc
	v_add_u32_e32 v4, 1, v1
	v_cmp_ge_u32_e32 vcc, v3, v2
	v_add_u32_e32 v3, 1, v5
	s_nop 0
	v_cndmask_b32_e32 v1, v1, v4, vcc
	v_mul_lo_u32 v4, v2, v1
	v_add_u32_e32 v2, v4, v2
	v_cmp_ne_u32_e32 vcc, v3, v2
	s_and_saveexec_b64 s[0:1], vcc
	s_xor_b64 s[8:9], exec, s[0:1]
	s_cbranch_execz .LBB0_135
	s_waitcnt lgkmcnt(0)
	v_mov_b32_e32 v0, 0
	s_add_u32 s12, s4, 0x3500
	s_addc_u32 s13, s5, 0
	global_load_dword v0, v0, s[12:13] sc1
	s_waitcnt vmcnt(0)
	v_cmp_eq_u32_e32 vcc, v0, v1
	s_and_saveexec_b64 s[10:11], vcc
	s_cbranch_execz .LBB0_134
	s_mov_b32 s0, 1
	s_mov_b64 s[14:15], 0
	v_mov_b32_e32 v0, 0
	s_branch .LBB0_125

.LBB0_583:
	s_or_b64 exec, exec, s[10:11]
	v_cvt_f32_u32_e32 v5, v3
	s_waitcnt vmcnt(0)
	v_readfirstlane_b32 s0, v4
	v_sub_u32_e32 v4, 0, v3
	v_rcp_iflag_f32_e32 v5, v5
	v_add_u32_e32 v6, s0, v0
	v_mul_f32_e32 v5, 0x4f7ffffe, v5
	v_cvt_u32_f32_e32 v5, v5
	v_mul_lo_u32 v0, v4, v5
	v_mul_hi_u32 v0, v5, v0
	v_add_u32_e32 v0, v5, v0
	v_mul_hi_u32 v0, v6, v0
	v_mul_lo_u32 v4, v0, v3
	v_sub_u32_e32 v4, v6, v4
	v_add_u32_e32 v5, 1, v0
	v_cmp_ge_u32_e32 vcc, v4, v3
	s_nop 1
	v_cndmask_b32_e32 v0, v0, v5, vcc
	v_sub_u32_e32 v5, v4, v3
	v_cndmask_b32_e32 v4, v4, v5, vcc
	v_add_u32_e32 v5, 1, v0
	v_cmp_ge_u32_e32 vcc, v4, v3
	v_add_u32_e32 v4, 1, v6
	s_nop 0
	v_cndmask_b32_e32 v0, v0, v5, vcc
	v_mul_lo_u32 v5, v3, v0
	v_add_u32_e32 v3, v5, v3
	v_cmp_ne_u32_e32 vcc, v4, v3
	s_and_saveexec_b64 s[0:1], vcc
	s_xor_b64 s[8:9], exec, s[0:1]
	s_cbranch_execz .LBB0_597
	s_waitcnt lgkmcnt(0)
	s_add_u32 s12, s4, 0x3500
	s_addc_u32 s13, s5, 0
	global_load_dword v2, v1, s[12:13] sc1
	s_waitcnt vmcnt(0)
	v_cmp_eq_u32_e32 vcc, v2, v0
	s_and_saveexec_b64 s[10:11], vcc
	s_cbranch_execz .LBB0_596
	s_mov_b32 s0, 1
	s_mov_b64 s[14:15], 0
	s_branch .LBB0_587

.LBB0_1204:
	s_or_b64 exec, exec, s[12:13]
	v_cvt_f32_u32_e32 v5, v3
	s_waitcnt vmcnt(0)
	v_readfirstlane_b32 s0, v4
	v_sub_u32_e32 v4, 0, v3
	v_rcp_iflag_f32_e32 v5, v5
	v_add_u32_e32 v6, s0, v0
	v_mul_f32_e32 v5, 0x4f7ffffe, v5
	v_cvt_u32_f32_e32 v5, v5
	v_mul_lo_u32 v0, v4, v5
	v_mul_hi_u32 v0, v5, v0
	v_add_u32_e32 v0, v5, v0
	v_mul_hi_u32 v0, v6, v0
	v_mul_lo_u32 v4, v0, v3
	v_sub_u32_e32 v4, v6, v4
	v_add_u32_e32 v5, 1, v0
	v_cmp_ge_u32_e32 vcc, v4, v3
	s_nop 1
	v_cndmask_b32_e32 v0, v0, v5, vcc
	v_sub_u32_e32 v5, v4, v3
	v_cndmask_b32_e32 v4, v4, v5, vcc
	v_add_u32_e32 v5, 1, v0
	v_cmp_ge_u32_e32 vcc, v4, v3
	v_add_u32_e32 v4, 1, v6
	s_nop 0
	v_cndmask_b32_e32 v0, v0, v5, vcc
	v_mul_lo_u32 v5, v3, v0
	v_add_u32_e32 v3, v5, v3
	v_cmp_ne_u32_e32 vcc, v4, v3
	s_and_saveexec_b64 s[0:1], vcc
	s_xor_b64 s[10:11], exec, s[0:1]
	s_cbranch_execz .LBB0_1218
	s_waitcnt lgkmcnt(0)
	s_add_u32 s14, s4, 0x3500
	s_addc_u32 s15, s5, 0
	global_load_dword v2, v1, s[14:15] sc1
	s_waitcnt vmcnt(0)
	v_cmp_eq_u32_e32 vcc, v2, v0
	s_and_saveexec_b64 s[12:13], vcc
	s_cbranch_execz .LBB0_1217
	s_mov_b32 s0, 1
	s_mov_b64 s[16:17], 0
	s_branch .LBB0_1208
